# v054 + GEMM loops: flips deleted, one static s_setprio 1 for waves 0-3 at kernel entry
# speedup vs baseline: 1.0010x; 1.0010x over previous
_Z6mk_fwd4Args:
	v_readfirstlane_b32 s100, v0
	s_nop 3
	s_and_b32 s100, s100, 0x3ff
	s_lshr_b32 s100, s100, 6
	s_cmp_ge_u32 s100, 4
	s_cbranch_scc1 .Lprio_done
	s_setprio 1
